# combo + init phase with hand-written modulation GEMV loop (32-64 row loads in flight) and hand-written double-buffered layer-0 weight transposer
# speedup vs baseline: 1.0091x; 1.0091x over previous
; #define LAS __attribute__((address_space(3)))
; __device__ __forceinline__ void init_phase(const Args& a, LAS unsigned char* lds, int G) {
;     ...
;     for (int item = blockIdx.x; item < 384; item += G) {
;         const int layer = item / 96, n0 = (item % 96) * 64, ks = tid >> 6, nn = tid & 63;
;         float acc0 = 0.f, acc1 = 0.f, acc2 = 0.f, acc3 = 0.f, acc4 = 0.f;
;         const float* wp = a.in[4] + ((size_t)layer * 2048 + ks * 256) * 6144 + n0 + nn;
;         const LAS float* sp = sc + ks * 256;
; #pragma unroll 32
;         for (int kk = 0; kk < 256; ++kk) {
;             const float w = wp[(size_t)kk * 6144];
;             acc0 += sp[kk] * w; acc1 += sp[2048 + kk] * w; acc2 += sp[4096 + kk] * w; acc3 += sp[6144 + kk] * w; acc4 += sp[8192 + kk] * w;
;         }
.LBB0_258:
	s_mul_hi_i32 s0, s26, 0x2aaaaaab
	s_lshr_b32 s1, s0, 31
	s_ashr_i32 s0, s0, 4
	s_add_i32 s18, s0, s1
	s_mul_i32 s0, s18, 0x60
	s_sub_i32 s0, s26, s0
	s_ashr_i32 s19, s18, 31
	s_lshl_b32 s14, s0, 6
	s_lshl_b64 s[0:1], s[18:19], 11
	v_lshl_add_u64 v[0:1], s[0:1], 0, v[84:85]
	v_mov_b64_e32 v[2:3], s[6:7]
	v_mad_u64_u32 v[2:3], s[0:1], v0, s11, v[2:3]
	v_mad_i32_i24 v3, v1, s11, v3
	s_ashr_i32 s15, s14, 31
	v_lshl_add_u64 v[0:1], s[14:15], 2, v[2:3]
	v_mov_b32_e32 v81, 0
	v_lshl_add_u64 v[90:91], v[0:1], 0, v[96:97]
	s_mov_b64 s[24:25], 0
	v_mov_b32_e32 v83, v79
	v_mov_b32_e32 v60, 0
	v_mov_b32_e32 v61, v81
	v_mov_b32_e32 v4, 0
	v_mov_b32_e32 v5, v81
	s_mov_b32 s19, 0x12000
	s_mov_b32 s23, 0x1e000
	s_mov_b32 s27, 0x24000
	s_mov_b32 s28, 0x2a000
	s_mov_b32 s29, 0x36000
	s_mov_b32 s30, 0x42000
	s_mov_b32 s31, 0x4e000
	s_mov_b32 s36, 0x54000
	s_mov_b32 s37, 0x5a000
	s_mov_b32 s38, 0x66000
	s_mov_b32 s39, 0x6c000
	s_mov_b32 s40, 0xb4000
	s_mov_b32 s41, 0xa8000
	v_readfirstlane_b32 s0, v90
	v_readfirstlane_b32 s1, v91
	v_mov_b32_e32 v120, 0
	v_mov_b32_e32 v121, 0
	v_mov_b32_e32 v122, 0
	v_mov_b32_e32 v123, 0
	v_mov_b32_e32 v124, 0
	s_mov_b32 s24, 0
	s_nop 1
	global_load_dword v0, v96, s[0:1]
	s_add_u32 s0, s0, s11
	s_addc_u32 s1, s1, 0
	global_load_dword v1, v96, s[0:1]
	s_add_u32 s0, s0, s11
	s_addc_u32 s1, s1, 0
	global_load_dword v2, v96, s[0:1]
	s_add_u32 s0, s0, s11
	s_addc_u32 s1, s1, 0
	global_load_dword v3, v96, s[0:1]
	s_add_u32 s0, s0, s11
	s_addc_u32 s1, s1, 0
	global_load_dword v4, v96, s[0:1]
	s_add_u32 s0, s0, s11
	s_addc_u32 s1, s1, 0
	global_load_dword v5, v96, s[0:1]
	s_add_u32 s0, s0, s11
	s_addc_u32 s1, s1, 0
	global_load_dword v6, v96, s[0:1]
	s_add_u32 s0, s0, s11
	s_addc_u32 s1, s1, 0
	global_load_dword v7, v96, s[0:1]
	s_add_u32 s0, s0, s11
	s_addc_u32 s1, s1, 0
	global_load_dword v8, v96, s[0:1]
	s_add_u32 s0, s0, s11
	s_addc_u32 s1, s1, 0
	global_load_dword v9, v96, s[0:1]
	s_add_u32 s0, s0, s11
	s_addc_u32 s1, s1, 0
	global_load_dword v10, v96, s[0:1]
	s_add_u32 s0, s0, s11
	s_addc_u32 s1, s1, 0
	global_load_dword v11, v96, s[0:1]
	s_add_u32 s0, s0, s11
	s_addc_u32 s1, s1, 0
	global_load_dword v12, v96, s[0:1]
	s_add_u32 s0, s0, s11
	s_addc_u32 s1, s1, 0
	global_load_dword v13, v96, s[0:1]
	s_add_u32 s0, s0, s11
	s_addc_u32 s1, s1, 0
	global_load_dword v14, v96, s[0:1]
	s_add_u32 s0, s0, s11
	s_addc_u32 s1, s1, 0
	global_load_dword v15, v96, s[0:1]
	s_add_u32 s0, s0, s11
	s_addc_u32 s1, s1, 0
	global_load_dword v16, v96, s[0:1]
	s_add_u32 s0, s0, s11
	s_addc_u32 s1, s1, 0
	global_load_dword v17, v96, s[0:1]
	s_add_u32 s0, s0, s11
	s_addc_u32 s1, s1, 0
	global_load_dword v18, v96, s[0:1]
	s_add_u32 s0, s0, s11
	s_addc_u32 s1, s1, 0
	global_load_dword v19, v96, s[0:1]
	s_add_u32 s0, s0, s11
	s_addc_u32 s1, s1, 0
	global_load_dword v20, v96, s[0:1]
	s_add_u32 s0, s0, s11
	s_addc_u32 s1, s1, 0
	global_load_dword v21, v96, s[0:1]
	s_add_u32 s0, s0, s11
	s_addc_u32 s1, s1, 0
	global_load_dword v22, v96, s[0:1]
	s_add_u32 s0, s0, s11
	s_addc_u32 s1, s1, 0
	global_load_dword v23, v96, s[0:1]
	s_add_u32 s0, s0, s11
	s_addc_u32 s1, s1, 0
	global_load_dword v24, v96, s[0:1]
	s_add_u32 s0, s0, s11
	s_addc_u32 s1, s1, 0
	global_load_dword v25, v96, s[0:1]
	s_add_u32 s0, s0, s11
	s_addc_u32 s1, s1, 0
	global_load_dword v26, v96, s[0:1]
	s_add_u32 s0, s0, s11
	s_addc_u32 s1, s1, 0
	global_load_dword v27, v96, s[0:1]
	s_add_u32 s0, s0, s11
	s_addc_u32 s1, s1, 0
	global_load_dword v28, v96, s[0:1]
	s_add_u32 s0, s0, s11
	s_addc_u32 s1, s1, 0
	global_load_dword v29, v96, s[0:1]
	s_add_u32 s0, s0, s11
	s_addc_u32 s1, s1, 0
	global_load_dword v30, v96, s[0:1]
	s_add_u32 s0, s0, s11
	s_addc_u32 s1, s1, 0
	global_load_dword v31, v96, s[0:1]
	s_add_u32 s0, s0, s11
	s_addc_u32 s1, s1, 0
.Lgv_loop:
	global_load_dword v32, v96, s[0:1]
	s_add_u32 s0, s0, s11
	s_addc_u32 s1, s1, 0
	global_load_dword v33, v96, s[0:1]
	s_add_u32 s0, s0, s11
	s_addc_u32 s1, s1, 0
	global_load_dword v34, v96, s[0:1]
	s_add_u32 s0, s0, s11
	s_addc_u32 s1, s1, 0
	global_load_dword v35, v96, s[0:1]
	s_add_u32 s0, s0, s11
	s_addc_u32 s1, s1, 0
	global_load_dword v36, v96, s[0:1]
	s_add_u32 s0, s0, s11
	s_addc_u32 s1, s1, 0
	global_load_dword v37, v96, s[0:1]
	s_add_u32 s0, s0, s11
	s_addc_u32 s1, s1, 0
	global_load_dword v38, v96, s[0:1]
	s_add_u32 s0, s0, s11
	s_addc_u32 s1, s1, 0
	global_load_dword v39, v96, s[0:1]
	s_add_u32 s0, s0, s11
	s_addc_u32 s1, s1, 0
	global_load_dword v40, v96, s[0:1]
	s_add_u32 s0, s0, s11
	s_addc_u32 s1, s1, 0
	global_load_dword v41, v96, s[0:1]
	s_add_u32 s0, s0, s11
	s_addc_u32 s1, s1, 0
	global_load_dword v42, v96, s[0:1]
	s_add_u32 s0, s0, s11
	s_addc_u32 s1, s1, 0
	global_load_dword v43, v96, s[0:1]
	s_add_u32 s0, s0, s11
	s_addc_u32 s1, s1, 0
	global_load_dword v44, v96, s[0:1]
	s_add_u32 s0, s0, s11
	s_addc_u32 s1, s1, 0
	global_load_dword v45, v96, s[0:1]
	s_add_u32 s0, s0, s11
	s_addc_u32 s1, s1, 0
	global_load_dword v46, v96, s[0:1]
	s_add_u32 s0, s0, s11
	s_addc_u32 s1, s1, 0
	global_load_dword v47, v96, s[0:1]
	s_add_u32 s0, s0, s11
	s_addc_u32 s1, s1, 0
	global_load_dword v48, v96, s[0:1]
	s_add_u32 s0, s0, s11
	s_addc_u32 s1, s1, 0
	global_load_dword v49, v96, s[0:1]
	s_add_u32 s0, s0, s11
	s_addc_u32 s1, s1, 0
	global_load_dword v50, v96, s[0:1]
	s_add_u32 s0, s0, s11
	s_addc_u32 s1, s1, 0
	global_load_dword v51, v96, s[0:1]
	s_add_u32 s0, s0, s11
	s_addc_u32 s1, s1, 0
	global_load_dword v52, v96, s[0:1]
	s_add_u32 s0, s0, s11
	s_addc_u32 s1, s1, 0
	global_load_dword v53, v96, s[0:1]
	s_add_u32 s0, s0, s11
	s_addc_u32 s1, s1, 0
	global_load_dword v54, v96, s[0:1]
	s_add_u32 s0, s0, s11
	s_addc_u32 s1, s1, 0
	global_load_dword v55, v96, s[0:1]
	s_add_u32 s0, s0, s11
	s_addc_u32 s1, s1, 0
	global_load_dword v56, v96, s[0:1]
	s_add_u32 s0, s0, s11
	s_addc_u32 s1, s1, 0
	global_load_dword v57, v96, s[0:1]
	s_add_u32 s0, s0, s11
	s_addc_u32 s1, s1, 0
	global_load_dword v58, v96, s[0:1]
	s_add_u32 s0, s0, s11
	s_addc_u32 s1, s1, 0
	global_load_dword v59, v96, s[0:1]
	s_add_u32 s0, s0, s11
	s_addc_u32 s1, s1, 0
	global_load_dword v60, v96, s[0:1]
	s_add_u32 s0, s0, s11
	s_addc_u32 s1, s1, 0
	global_load_dword v61, v96, s[0:1]
	s_add_u32 s0, s0, s11
	s_addc_u32 s1, s1, 0
	global_load_dword v62, v96, s[0:1]
	s_add_u32 s0, s0, s11
	s_addc_u32 s1, s1, 0
	global_load_dword v63, v96, s[0:1]
	s_add_u32 s0, s0, s11
	s_addc_u32 s1, s1, 0
	s_waitcnt vmcnt(32)
; __device__ __forceinline__ void init_phase(const Args& a, LAS unsigned char* lds, int G) {
;     ...
; #pragma unroll 32
;         for (int kk = 0; kk < 256; ++kk) {
;             const float w = wp[(size_t)kk * 6144];
;             acc0 += sp[kk] * w; acc1 += sp[2048 + kk] * w; acc2 += sp[4096 + kk] * w; acc3 += sp[6144 + kk] * w; acc4 += sp[8192 + kk] * w;
;         }
	ds_read_b128 v[98:101], v83 offset:0
	ds_read_b128 v[102:105], v83 offset:8192
	ds_read_b128 v[106:109], v83 offset:16384
	ds_read_b128 v[110:113], v83 offset:24576
	ds_read_b128 v[114:117], v83 offset:32768
	ds_read_b128 v[130:133], v83 offset:16
	ds_read_b128 v[134:137], v83 offset:8208
	ds_read_b128 v[138:141], v83 offset:16400
	ds_read_b128 v[142:145], v83 offset:24592
	ds_read_b128 v[146:149], v83 offset:32784
	s_waitcnt lgkmcnt(5)
	v_fmac_f32_e32 v120, v98, v0
	v_fmac_f32_e32 v121, v102, v0
	v_fmac_f32_e32 v122, v106, v0
	v_fmac_f32_e32 v123, v110, v0
	v_fmac_f32_e32 v124, v114, v0
	v_fmac_f32_e32 v120, v99, v1
	v_fmac_f32_e32 v121, v103, v1
	v_fmac_f32_e32 v122, v107, v1
	v_fmac_f32_e32 v123, v111, v1
	v_fmac_f32_e32 v124, v115, v1
	v_fmac_f32_e32 v120, v100, v2
	v_fmac_f32_e32 v121, v104, v2
	v_fmac_f32_e32 v122, v108, v2
	v_fmac_f32_e32 v123, v112, v2
	v_fmac_f32_e32 v124, v116, v2
	v_fmac_f32_e32 v120, v101, v3
	v_fmac_f32_e32 v121, v105, v3
	v_fmac_f32_e32 v122, v109, v3
	v_fmac_f32_e32 v123, v113, v3
	v_fmac_f32_e32 v124, v117, v3
	ds_read_b128 v[98:101], v83 offset:32
	ds_read_b128 v[102:105], v83 offset:8224
	ds_read_b128 v[106:109], v83 offset:16416
	ds_read_b128 v[110:113], v83 offset:24608
	ds_read_b128 v[114:117], v83 offset:32800
	s_waitcnt lgkmcnt(5)
	v_fmac_f32_e32 v120, v130, v4
	v_fmac_f32_e32 v121, v134, v4
	v_fmac_f32_e32 v122, v138, v4
	v_fmac_f32_e32 v123, v142, v4
	v_fmac_f32_e32 v124, v146, v4
	v_fmac_f32_e32 v120, v131, v5
	v_fmac_f32_e32 v121, v135, v5
	v_fmac_f32_e32 v122, v139, v5
	v_fmac_f32_e32 v123, v143, v5
	v_fmac_f32_e32 v124, v147, v5
	v_fmac_f32_e32 v120, v132, v6
	v_fmac_f32_e32 v121, v136, v6
	v_fmac_f32_e32 v122, v140, v6
	v_fmac_f32_e32 v123, v144, v6
	v_fmac_f32_e32 v124, v148, v6
	v_fmac_f32_e32 v120, v133, v7
	v_fmac_f32_e32 v121, v137, v7
	v_fmac_f32_e32 v122, v141, v7
	v_fmac_f32_e32 v123, v145, v7
	v_fmac_f32_e32 v124, v149, v7
	ds_read_b128 v[130:133], v83 offset:48
	ds_read_b128 v[134:137], v83 offset:8240
	ds_read_b128 v[138:141], v83 offset:16432
	ds_read_b128 v[142:145], v83 offset:24624
	ds_read_b128 v[146:149], v83 offset:32816
	s_waitcnt lgkmcnt(5)
	v_fmac_f32_e32 v120, v98, v8
	v_fmac_f32_e32 v121, v102, v8
	v_fmac_f32_e32 v122, v106, v8
	v_fmac_f32_e32 v123, v110, v8
	v_fmac_f32_e32 v124, v114, v8
	v_fmac_f32_e32 v120, v99, v9
	v_fmac_f32_e32 v121, v103, v9
	v_fmac_f32_e32 v122, v107, v9
	v_fmac_f32_e32 v123, v111, v9
	v_fmac_f32_e32 v124, v115, v9
	v_fmac_f32_e32 v120, v100, v10
	v_fmac_f32_e32 v121, v104, v10
	v_fmac_f32_e32 v122, v108, v10
	v_fmac_f32_e32 v123, v112, v10
	v_fmac_f32_e32 v124, v116, v10
	v_fmac_f32_e32 v120, v101, v11
	v_fmac_f32_e32 v121, v105, v11
	v_fmac_f32_e32 v122, v109, v11
	v_fmac_f32_e32 v123, v113, v11
	v_fmac_f32_e32 v124, v117, v11
	ds_read_b128 v[98:101], v83 offset:64
	ds_read_b128 v[102:105], v83 offset:8256
	ds_read_b128 v[106:109], v83 offset:16448
	ds_read_b128 v[110:113], v83 offset:24640
	ds_read_b128 v[114:117], v83 offset:32832
	s_waitcnt lgkmcnt(5)
	v_fmac_f32_e32 v120, v130, v12
	v_fmac_f32_e32 v121, v134, v12
	v_fmac_f32_e32 v122, v138, v12
	v_fmac_f32_e32 v123, v142, v12
	v_fmac_f32_e32 v124, v146, v12
	v_fmac_f32_e32 v120, v131, v13
	v_fmac_f32_e32 v121, v135, v13
	v_fmac_f32_e32 v122, v139, v13
	v_fmac_f32_e32 v123, v143, v13
	v_fmac_f32_e32 v124, v147, v13
	v_fmac_f32_e32 v120, v132, v14
	v_fmac_f32_e32 v121, v136, v14
	v_fmac_f32_e32 v122, v140, v14
	v_fmac_f32_e32 v123, v144, v14
	v_fmac_f32_e32 v124, v148, v14
	v_fmac_f32_e32 v120, v133, v15
	v_fmac_f32_e32 v121, v137, v15
	v_fmac_f32_e32 v122, v141, v15
	v_fmac_f32_e32 v123, v145, v15
	v_fmac_f32_e32 v124, v149, v15
	ds_read_b128 v[130:133], v83 offset:80
	ds_read_b128 v[134:137], v83 offset:8272
	ds_read_b128 v[138:141], v83 offset:16464
	ds_read_b128 v[142:145], v83 offset:24656
	ds_read_b128 v[146:149], v83 offset:32848
	s_waitcnt lgkmcnt(5)
	v_fmac_f32_e32 v120, v98, v16
	v_fmac_f32_e32 v121, v102, v16
	v_fmac_f32_e32 v122, v106, v16
	v_fmac_f32_e32 v123, v110, v16
	v_fmac_f32_e32 v124, v114, v16
	v_fmac_f32_e32 v120, v99, v17
	v_fmac_f32_e32 v121, v103, v17
	v_fmac_f32_e32 v122, v107, v17
	v_fmac_f32_e32 v123, v111, v17
	v_fmac_f32_e32 v124, v115, v17
	v_fmac_f32_e32 v120, v100, v18
	v_fmac_f32_e32 v121, v104, v18
	v_fmac_f32_e32 v122, v108, v18
	v_fmac_f32_e32 v123, v112, v18
	v_fmac_f32_e32 v124, v116, v18
	v_fmac_f32_e32 v120, v101, v19
	v_fmac_f32_e32 v121, v105, v19
	v_fmac_f32_e32 v122, v109, v19
	v_fmac_f32_e32 v123, v113, v19
	v_fmac_f32_e32 v124, v117, v19
	ds_read_b128 v[98:101], v83 offset:96
	ds_read_b128 v[102:105], v83 offset:8288
	ds_read_b128 v[106:109], v83 offset:16480
	ds_read_b128 v[110:113], v83 offset:24672
	ds_read_b128 v[114:117], v83 offset:32864
	s_waitcnt lgkmcnt(5)
	v_fmac_f32_e32 v120, v130, v20
	v_fmac_f32_e32 v121, v134, v20
	v_fmac_f32_e32 v122, v138, v20
	v_fmac_f32_e32 v123, v142, v20
	v_fmac_f32_e32 v124, v146, v20
	v_fmac_f32_e32 v120, v131, v21
	v_fmac_f32_e32 v121, v135, v21
	v_fmac_f32_e32 v122, v139, v21
	v_fmac_f32_e32 v123, v143, v21
	v_fmac_f32_e32 v124, v147, v21
	v_fmac_f32_e32 v120, v132, v22
	v_fmac_f32_e32 v121, v136, v22
	v_fmac_f32_e32 v122, v140, v22
	v_fmac_f32_e32 v123, v144, v22
	v_fmac_f32_e32 v124, v148, v22
	v_fmac_f32_e32 v120, v133, v23
	v_fmac_f32_e32 v121, v137, v23
	v_fmac_f32_e32 v122, v141, v23
	v_fmac_f32_e32 v123, v145, v23
	v_fmac_f32_e32 v124, v149, v23
	ds_read_b128 v[130:133], v83 offset:112
	ds_read_b128 v[134:137], v83 offset:8304
	ds_read_b128 v[138:141], v83 offset:16496
	ds_read_b128 v[142:145], v83 offset:24688
	ds_read_b128 v[146:149], v83 offset:32880
	s_waitcnt lgkmcnt(5)
	v_fmac_f32_e32 v120, v98, v24
	v_fmac_f32_e32 v121, v102, v24
	v_fmac_f32_e32 v122, v106, v24
	v_fmac_f32_e32 v123, v110, v24
	v_fmac_f32_e32 v124, v114, v24
	v_fmac_f32_e32 v120, v99, v25
	v_fmac_f32_e32 v121, v103, v25
	v_fmac_f32_e32 v122, v107, v25
	v_fmac_f32_e32 v123, v111, v25
	v_fmac_f32_e32 v124, v115, v25
	v_fmac_f32_e32 v120, v100, v26
	v_fmac_f32_e32 v121, v104, v26
	v_fmac_f32_e32 v122, v108, v26
	v_fmac_f32_e32 v123, v112, v26
	v_fmac_f32_e32 v124, v116, v26
	v_fmac_f32_e32 v120, v101, v27
	v_fmac_f32_e32 v121, v105, v27
	v_fmac_f32_e32 v122, v109, v27
	v_fmac_f32_e32 v123, v113, v27
	v_fmac_f32_e32 v124, v117, v27
	s_waitcnt lgkmcnt(0)
	v_fmac_f32_e32 v120, v130, v28
	v_fmac_f32_e32 v121, v134, v28
	v_fmac_f32_e32 v122, v138, v28
	v_fmac_f32_e32 v123, v142, v28
	v_fmac_f32_e32 v124, v146, v28
	v_fmac_f32_e32 v120, v131, v29
	v_fmac_f32_e32 v121, v135, v29
	v_fmac_f32_e32 v122, v139, v29
	v_fmac_f32_e32 v123, v143, v29
	v_fmac_f32_e32 v124, v147, v29
	v_fmac_f32_e32 v120, v132, v30
	v_fmac_f32_e32 v121, v136, v30
	v_fmac_f32_e32 v122, v140, v30
	v_fmac_f32_e32 v123, v144, v30
	v_fmac_f32_e32 v124, v148, v30
	v_fmac_f32_e32 v120, v133, v31
	v_fmac_f32_e32 v121, v137, v31
	v_fmac_f32_e32 v122, v141, v31
	v_fmac_f32_e32 v123, v145, v31
	v_fmac_f32_e32 v124, v149, v31
	s_cmp_eq_u32 s24, 3
	s_cbranch_scc1 .Lgv_last
; __device__ __forceinline__ void init_phase(const Args& a, LAS unsigned char* lds, int G) {
;     ...
; #pragma unroll 32
;         for (int kk = 0; kk < 256; ++kk) {
;             const float w = wp[(size_t)kk * 6144];
;             acc0 += sp[kk] * w; acc1 += sp[2048 + kk] * w; acc2 += sp[4096 + kk] * w; acc3 += sp[6144 + kk] * w; acc4 += sp[8192 + kk] * w;
;         }
	global_load_dword v0, v96, s[0:1]
	s_add_u32 s0, s0, s11
	s_addc_u32 s1, s1, 0
	global_load_dword v1, v96, s[0:1]
	s_add_u32 s0, s0, s11
	s_addc_u32 s1, s1, 0
	global_load_dword v2, v96, s[0:1]
	s_add_u32 s0, s0, s11
	s_addc_u32 s1, s1, 0
	global_load_dword v3, v96, s[0:1]
	s_add_u32 s0, s0, s11
	s_addc_u32 s1, s1, 0
	global_load_dword v4, v96, s[0:1]
	s_add_u32 s0, s0, s11
	s_addc_u32 s1, s1, 0
	global_load_dword v5, v96, s[0:1]
	s_add_u32 s0, s0, s11
	s_addc_u32 s1, s1, 0
	global_load_dword v6, v96, s[0:1]
	s_add_u32 s0, s0, s11
	s_addc_u32 s1, s1, 0
	global_load_dword v7, v96, s[0:1]
	s_add_u32 s0, s0, s11
	s_addc_u32 s1, s1, 0
	global_load_dword v8, v96, s[0:1]
	s_add_u32 s0, s0, s11
	s_addc_u32 s1, s1, 0
	global_load_dword v9, v96, s[0:1]
	s_add_u32 s0, s0, s11
	s_addc_u32 s1, s1, 0
	global_load_dword v10, v96, s[0:1]
	s_add_u32 s0, s0, s11
	s_addc_u32 s1, s1, 0
	global_load_dword v11, v96, s[0:1]
	s_add_u32 s0, s0, s11
	s_addc_u32 s1, s1, 0
	global_load_dword v12, v96, s[0:1]
	s_add_u32 s0, s0, s11
	s_addc_u32 s1, s1, 0
	global_load_dword v13, v96, s[0:1]
	s_add_u32 s0, s0, s11
	s_addc_u32 s1, s1, 0
	global_load_dword v14, v96, s[0:1]
	s_add_u32 s0, s0, s11
	s_addc_u32 s1, s1, 0
	global_load_dword v15, v96, s[0:1]
	s_add_u32 s0, s0, s11
	s_addc_u32 s1, s1, 0
	global_load_dword v16, v96, s[0:1]
	s_add_u32 s0, s0, s11
	s_addc_u32 s1, s1, 0
	global_load_dword v17, v96, s[0:1]
	s_add_u32 s0, s0, s11
	s_addc_u32 s1, s1, 0
	global_load_dword v18, v96, s[0:1]
	s_add_u32 s0, s0, s11
	s_addc_u32 s1, s1, 0
	global_load_dword v19, v96, s[0:1]
	s_add_u32 s0, s0, s11
	s_addc_u32 s1, s1, 0
	global_load_dword v20, v96, s[0:1]
	s_add_u32 s0, s0, s11
	s_addc_u32 s1, s1, 0
	global_load_dword v21, v96, s[0:1]
	s_add_u32 s0, s0, s11
	s_addc_u32 s1, s1, 0
	global_load_dword v22, v96, s[0:1]
	s_add_u32 s0, s0, s11
	s_addc_u32 s1, s1, 0
	global_load_dword v23, v96, s[0:1]
	s_add_u32 s0, s0, s11
	s_addc_u32 s1, s1, 0
	global_load_dword v24, v96, s[0:1]
	s_add_u32 s0, s0, s11
	s_addc_u32 s1, s1, 0
	global_load_dword v25, v96, s[0:1]
	s_add_u32 s0, s0, s11
	s_addc_u32 s1, s1, 0
	global_load_dword v26, v96, s[0:1]
	s_add_u32 s0, s0, s11
	s_addc_u32 s1, s1, 0
	global_load_dword v27, v96, s[0:1]
	s_add_u32 s0, s0, s11
	s_addc_u32 s1, s1, 0
	global_load_dword v28, v96, s[0:1]
	s_add_u32 s0, s0, s11
	s_addc_u32 s1, s1, 0
	global_load_dword v29, v96, s[0:1]
	s_add_u32 s0, s0, s11
	s_addc_u32 s1, s1, 0
	global_load_dword v30, v96, s[0:1]
	s_add_u32 s0, s0, s11
	s_addc_u32 s1, s1, 0
	global_load_dword v31, v96, s[0:1]
	s_add_u32 s0, s0, s11
	s_addc_u32 s1, s1, 0
	s_waitcnt vmcnt(32)
	ds_read_b128 v[98:101], v83 offset:128
	ds_read_b128 v[102:105], v83 offset:8320
	ds_read_b128 v[106:109], v83 offset:16512
	ds_read_b128 v[110:113], v83 offset:24704
	ds_read_b128 v[114:117], v83 offset:32896
	ds_read_b128 v[130:133], v83 offset:144
	ds_read_b128 v[134:137], v83 offset:8336
	ds_read_b128 v[138:141], v83 offset:16528
	ds_read_b128 v[142:145], v83 offset:24720
	ds_read_b128 v[146:149], v83 offset:32912
	s_waitcnt lgkmcnt(5)
	v_fmac_f32_e32 v120, v98, v32
	v_fmac_f32_e32 v121, v102, v32
	v_fmac_f32_e32 v122, v106, v32
	v_fmac_f32_e32 v123, v110, v32
	v_fmac_f32_e32 v124, v114, v32
	v_fmac_f32_e32 v120, v99, v33
	v_fmac_f32_e32 v121, v103, v33
	v_fmac_f32_e32 v122, v107, v33
	v_fmac_f32_e32 v123, v111, v33
	v_fmac_f32_e32 v124, v115, v33
	v_fmac_f32_e32 v120, v100, v34
	v_fmac_f32_e32 v121, v104, v34
	v_fmac_f32_e32 v122, v108, v34
	v_fmac_f32_e32 v123, v112, v34
	v_fmac_f32_e32 v124, v116, v34
	v_fmac_f32_e32 v120, v101, v35
	v_fmac_f32_e32 v121, v105, v35
	v_fmac_f32_e32 v122, v109, v35
	v_fmac_f32_e32 v123, v113, v35
	v_fmac_f32_e32 v124, v117, v35
	ds_read_b128 v[98:101], v83 offset:160
	ds_read_b128 v[102:105], v83 offset:8352
	ds_read_b128 v[106:109], v83 offset:16544
	ds_read_b128 v[110:113], v83 offset:24736
	ds_read_b128 v[114:117], v83 offset:32928
	s_waitcnt lgkmcnt(5)
	v_fmac_f32_e32 v120, v130, v36
	v_fmac_f32_e32 v121, v134, v36
	v_fmac_f32_e32 v122, v138, v36
	v_fmac_f32_e32 v123, v142, v36
	v_fmac_f32_e32 v124, v146, v36
	v_fmac_f32_e32 v120, v131, v37
	v_fmac_f32_e32 v121, v135, v37
	v_fmac_f32_e32 v122, v139, v37
	v_fmac_f32_e32 v123, v143, v37
	v_fmac_f32_e32 v124, v147, v37
	v_fmac_f32_e32 v120, v132, v38
	v_fmac_f32_e32 v121, v136, v38
	v_fmac_f32_e32 v122, v140, v38
	v_fmac_f32_e32 v123, v144, v38
	v_fmac_f32_e32 v124, v148, v38
	v_fmac_f32_e32 v120, v133, v39
	v_fmac_f32_e32 v121, v137, v39
	v_fmac_f32_e32 v122, v141, v39
	v_fmac_f32_e32 v123, v145, v39
	v_fmac_f32_e32 v124, v149, v39
	ds_read_b128 v[130:133], v83 offset:176
	ds_read_b128 v[134:137], v83 offset:8368
	ds_read_b128 v[138:141], v83 offset:16560
	ds_read_b128 v[142:145], v83 offset:24752
	ds_read_b128 v[146:149], v83 offset:32944
	s_waitcnt lgkmcnt(5)
	v_fmac_f32_e32 v120, v98, v40
	v_fmac_f32_e32 v121, v102, v40
	v_fmac_f32_e32 v122, v106, v40
	v_fmac_f32_e32 v123, v110, v40
	v_fmac_f32_e32 v124, v114, v40
	v_fmac_f32_e32 v120, v99, v41
	v_fmac_f32_e32 v121, v103, v41
	v_fmac_f32_e32 v122, v107, v41
	v_fmac_f32_e32 v123, v111, v41
	v_fmac_f32_e32 v124, v115, v41
	v_fmac_f32_e32 v120, v100, v42
	v_fmac_f32_e32 v121, v104, v42
	v_fmac_f32_e32 v122, v108, v42
	v_fmac_f32_e32 v123, v112, v42
	v_fmac_f32_e32 v124, v116, v42
	v_fmac_f32_e32 v120, v101, v43
	v_fmac_f32_e32 v121, v105, v43
	v_fmac_f32_e32 v122, v109, v43
	v_fmac_f32_e32 v123, v113, v43
	v_fmac_f32_e32 v124, v117, v43
	ds_read_b128 v[98:101], v83 offset:192
	ds_read_b128 v[102:105], v83 offset:8384
	ds_read_b128 v[106:109], v83 offset:16576
	ds_read_b128 v[110:113], v83 offset:24768
	ds_read_b128 v[114:117], v83 offset:32960
	s_waitcnt lgkmcnt(5)
; __device__ __forceinline__ void init_phase(const Args& a, LAS unsigned char* lds, int G) {
;     ...
; #pragma unroll 32
;         for (int kk = 0; kk < 256; ++kk) {
;             const float w = wp[(size_t)kk * 6144];
;             acc0 += sp[kk] * w; acc1 += sp[2048 + kk] * w; acc2 += sp[4096 + kk] * w; acc3 += sp[6144 + kk] * w; acc4 += sp[8192 + kk] * w;
;         }
	v_fmac_f32_e32 v120, v130, v44
	v_fmac_f32_e32 v121, v134, v44
	v_fmac_f32_e32 v122, v138, v44
	v_fmac_f32_e32 v123, v142, v44
	v_fmac_f32_e32 v124, v146, v44
	v_fmac_f32_e32 v120, v131, v45
	v_fmac_f32_e32 v121, v135, v45
	v_fmac_f32_e32 v122, v139, v45
	v_fmac_f32_e32 v123, v143, v45
	v_fmac_f32_e32 v124, v147, v45
	v_fmac_f32_e32 v120, v132, v46
	v_fmac_f32_e32 v121, v136, v46
	v_fmac_f32_e32 v122, v140, v46
	v_fmac_f32_e32 v123, v144, v46
	v_fmac_f32_e32 v124, v148, v46
	v_fmac_f32_e32 v120, v133, v47
	v_fmac_f32_e32 v121, v137, v47
	v_fmac_f32_e32 v122, v141, v47
	v_fmac_f32_e32 v123, v145, v47
	v_fmac_f32_e32 v124, v149, v47
	ds_read_b128 v[130:133], v83 offset:208
	ds_read_b128 v[134:137], v83 offset:8400
	ds_read_b128 v[138:141], v83 offset:16592
	ds_read_b128 v[142:145], v83 offset:24784
	ds_read_b128 v[146:149], v83 offset:32976
	s_waitcnt lgkmcnt(5)
	v_fmac_f32_e32 v120, v98, v48
	v_fmac_f32_e32 v121, v102, v48
	v_fmac_f32_e32 v122, v106, v48
	v_fmac_f32_e32 v123, v110, v48
	v_fmac_f32_e32 v124, v114, v48
	v_fmac_f32_e32 v120, v99, v49
	v_fmac_f32_e32 v121, v103, v49
	v_fmac_f32_e32 v122, v107, v49
	v_fmac_f32_e32 v123, v111, v49
	v_fmac_f32_e32 v124, v115, v49
	v_fmac_f32_e32 v120, v100, v50
	v_fmac_f32_e32 v121, v104, v50
	v_fmac_f32_e32 v122, v108, v50
	v_fmac_f32_e32 v123, v112, v50
	v_fmac_f32_e32 v124, v116, v50
	v_fmac_f32_e32 v120, v101, v51
	v_fmac_f32_e32 v121, v105, v51
	v_fmac_f32_e32 v122, v109, v51
	v_fmac_f32_e32 v123, v113, v51
	v_fmac_f32_e32 v124, v117, v51
	ds_read_b128 v[98:101], v83 offset:224
	ds_read_b128 v[102:105], v83 offset:8416
	ds_read_b128 v[106:109], v83 offset:16608
	ds_read_b128 v[110:113], v83 offset:24800
	ds_read_b128 v[114:117], v83 offset:32992
	s_waitcnt lgkmcnt(5)
	v_fmac_f32_e32 v120, v130, v52
	v_fmac_f32_e32 v121, v134, v52
	v_fmac_f32_e32 v122, v138, v52
	v_fmac_f32_e32 v123, v142, v52
	v_fmac_f32_e32 v124, v146, v52
	v_fmac_f32_e32 v120, v131, v53
	v_fmac_f32_e32 v121, v135, v53
	v_fmac_f32_e32 v122, v139, v53
	v_fmac_f32_e32 v123, v143, v53
	v_fmac_f32_e32 v124, v147, v53
	v_fmac_f32_e32 v120, v132, v54
	v_fmac_f32_e32 v121, v136, v54
	v_fmac_f32_e32 v122, v140, v54
	v_fmac_f32_e32 v123, v144, v54
	v_fmac_f32_e32 v124, v148, v54
	v_fmac_f32_e32 v120, v133, v55
	v_fmac_f32_e32 v121, v137, v55
	v_fmac_f32_e32 v122, v141, v55
	v_fmac_f32_e32 v123, v145, v55
	v_fmac_f32_e32 v124, v149, v55
	ds_read_b128 v[130:133], v83 offset:240
	ds_read_b128 v[134:137], v83 offset:8432
	ds_read_b128 v[138:141], v83 offset:16624
	ds_read_b128 v[142:145], v83 offset:24816
	ds_read_b128 v[146:149], v83 offset:33008
	s_waitcnt lgkmcnt(5)
	v_fmac_f32_e32 v120, v98, v56
	v_fmac_f32_e32 v121, v102, v56
	v_fmac_f32_e32 v122, v106, v56
	v_fmac_f32_e32 v123, v110, v56
	v_fmac_f32_e32 v124, v114, v56
	v_fmac_f32_e32 v120, v99, v57
	v_fmac_f32_e32 v121, v103, v57
	v_fmac_f32_e32 v122, v107, v57
	v_fmac_f32_e32 v123, v111, v57
	v_fmac_f32_e32 v124, v115, v57
	v_fmac_f32_e32 v120, v100, v58
	v_fmac_f32_e32 v121, v104, v58
	v_fmac_f32_e32 v122, v108, v58
	v_fmac_f32_e32 v123, v112, v58
	v_fmac_f32_e32 v124, v116, v58
	v_fmac_f32_e32 v120, v101, v59
	v_fmac_f32_e32 v121, v105, v59
	v_fmac_f32_e32 v122, v109, v59
	v_fmac_f32_e32 v123, v113, v59
	v_fmac_f32_e32 v124, v117, v59
	s_waitcnt lgkmcnt(0)
	v_fmac_f32_e32 v120, v130, v60
	v_fmac_f32_e32 v121, v134, v60
	v_fmac_f32_e32 v122, v138, v60
	v_fmac_f32_e32 v123, v142, v60
	v_fmac_f32_e32 v124, v146, v60
	v_fmac_f32_e32 v120, v131, v61
	v_fmac_f32_e32 v121, v135, v61
	v_fmac_f32_e32 v122, v139, v61
	v_fmac_f32_e32 v123, v143, v61
	v_fmac_f32_e32 v124, v147, v61
	v_fmac_f32_e32 v120, v132, v62
	v_fmac_f32_e32 v121, v136, v62
	v_fmac_f32_e32 v122, v140, v62
	v_fmac_f32_e32 v123, v144, v62
	v_fmac_f32_e32 v124, v148, v62
	v_fmac_f32_e32 v120, v133, v63
	v_fmac_f32_e32 v121, v137, v63
	v_fmac_f32_e32 v122, v141, v63
	v_fmac_f32_e32 v123, v145, v63
	v_fmac_f32_e32 v124, v149, v63
	v_add_u32_e32 v83, 0x100, v83
	s_add_i32 s24, s24, 1
	s_branch .Lgv_loop
.Lgv_last:
	s_waitcnt vmcnt(0)
	ds_read_b128 v[98:101], v83 offset:128
	ds_read_b128 v[102:105], v83 offset:8320
	ds_read_b128 v[106:109], v83 offset:16512
	ds_read_b128 v[110:113], v83 offset:24704
	ds_read_b128 v[114:117], v83 offset:32896
	ds_read_b128 v[130:133], v83 offset:144
	ds_read_b128 v[134:137], v83 offset:8336
	ds_read_b128 v[138:141], v83 offset:16528
	ds_read_b128 v[142:145], v83 offset:24720
	ds_read_b128 v[146:149], v83 offset:32912
	s_waitcnt lgkmcnt(5)
	v_fmac_f32_e32 v120, v98, v32
	v_fmac_f32_e32 v121, v102, v32
	v_fmac_f32_e32 v122, v106, v32
	v_fmac_f32_e32 v123, v110, v32
	v_fmac_f32_e32 v124, v114, v32
	v_fmac_f32_e32 v120, v99, v33
	v_fmac_f32_e32 v121, v103, v33
	v_fmac_f32_e32 v122, v107, v33
	v_fmac_f32_e32 v123, v111, v33
	v_fmac_f32_e32 v124, v115, v33
	v_fmac_f32_e32 v120, v100, v34
	v_fmac_f32_e32 v121, v104, v34
	v_fmac_f32_e32 v122, v108, v34
	v_fmac_f32_e32 v123, v112, v34
	v_fmac_f32_e32 v124, v116, v34
	v_fmac_f32_e32 v120, v101, v35
	v_fmac_f32_e32 v121, v105, v35
	v_fmac_f32_e32 v122, v109, v35
	v_fmac_f32_e32 v123, v113, v35
	v_fmac_f32_e32 v124, v117, v35
	ds_read_b128 v[98:101], v83 offset:160
	ds_read_b128 v[102:105], v83 offset:8352
	ds_read_b128 v[106:109], v83 offset:16544
	ds_read_b128 v[110:113], v83 offset:24736
	ds_read_b128 v[114:117], v83 offset:32928
	s_waitcnt lgkmcnt(5)
; __device__ __forceinline__ void init_phase(const Args& a, LAS unsigned char* lds, int G) {
;     ...
; #pragma unroll 32
;         for (int kk = 0; kk < 256; ++kk) {
;             const float w = wp[(size_t)kk * 6144];
;             acc0 += sp[kk] * w; acc1 += sp[2048 + kk] * w; acc2 += sp[4096 + kk] * w; acc3 += sp[6144 + kk] * w; acc4 += sp[8192 + kk] * w;
;         }
;         red[(ks * 5 + 0) * 64 + nn] = acc0; red[(ks * 5 + 1) * 64 + nn] = acc1; red[(ks * 5 + 2) * 64 + nn] = acc2; red[(ks * 5 + 3) * 64 + nn] = acc3; red[(ks * 5 + 4) * 64 + nn] = acc4;
;         __syncthreads();
	v_fmac_f32_e32 v120, v130, v36
	v_fmac_f32_e32 v121, v134, v36
	v_fmac_f32_e32 v122, v138, v36
	v_fmac_f32_e32 v123, v142, v36
	v_fmac_f32_e32 v124, v146, v36
	v_fmac_f32_e32 v120, v131, v37
	v_fmac_f32_e32 v121, v135, v37
	v_fmac_f32_e32 v122, v139, v37
	v_fmac_f32_e32 v123, v143, v37
	v_fmac_f32_e32 v124, v147, v37
	v_fmac_f32_e32 v120, v132, v38
	v_fmac_f32_e32 v121, v136, v38
	v_fmac_f32_e32 v122, v140, v38
	v_fmac_f32_e32 v123, v144, v38
	v_fmac_f32_e32 v124, v148, v38
	v_fmac_f32_e32 v120, v133, v39
	v_fmac_f32_e32 v121, v137, v39
	v_fmac_f32_e32 v122, v141, v39
	v_fmac_f32_e32 v123, v145, v39
	v_fmac_f32_e32 v124, v149, v39
	ds_read_b128 v[130:133], v83 offset:176
	ds_read_b128 v[134:137], v83 offset:8368
	ds_read_b128 v[138:141], v83 offset:16560
	ds_read_b128 v[142:145], v83 offset:24752
	ds_read_b128 v[146:149], v83 offset:32944
	s_waitcnt lgkmcnt(5)
	v_fmac_f32_e32 v120, v98, v40
	v_fmac_f32_e32 v121, v102, v40
	v_fmac_f32_e32 v122, v106, v40
	v_fmac_f32_e32 v123, v110, v40
	v_fmac_f32_e32 v124, v114, v40
	v_fmac_f32_e32 v120, v99, v41
	v_fmac_f32_e32 v121, v103, v41
	v_fmac_f32_e32 v122, v107, v41
	v_fmac_f32_e32 v123, v111, v41
	v_fmac_f32_e32 v124, v115, v41
	v_fmac_f32_e32 v120, v100, v42
	v_fmac_f32_e32 v121, v104, v42
	v_fmac_f32_e32 v122, v108, v42
	v_fmac_f32_e32 v123, v112, v42
	v_fmac_f32_e32 v124, v116, v42
	v_fmac_f32_e32 v120, v101, v43
	v_fmac_f32_e32 v121, v105, v43
	v_fmac_f32_e32 v122, v109, v43
	v_fmac_f32_e32 v123, v113, v43
	v_fmac_f32_e32 v124, v117, v43
	ds_read_b128 v[98:101], v83 offset:192
	ds_read_b128 v[102:105], v83 offset:8384
	ds_read_b128 v[106:109], v83 offset:16576
	ds_read_b128 v[110:113], v83 offset:24768
	ds_read_b128 v[114:117], v83 offset:32960
	s_waitcnt lgkmcnt(5)
	v_fmac_f32_e32 v120, v130, v44
	v_fmac_f32_e32 v121, v134, v44
	v_fmac_f32_e32 v122, v138, v44
	v_fmac_f32_e32 v123, v142, v44
	v_fmac_f32_e32 v124, v146, v44
	v_fmac_f32_e32 v120, v131, v45
	v_fmac_f32_e32 v121, v135, v45
	v_fmac_f32_e32 v122, v139, v45
	v_fmac_f32_e32 v123, v143, v45
	v_fmac_f32_e32 v124, v147, v45
	v_fmac_f32_e32 v120, v132, v46
	v_fmac_f32_e32 v121, v136, v46
	v_fmac_f32_e32 v122, v140, v46
	v_fmac_f32_e32 v123, v144, v46
	v_fmac_f32_e32 v124, v148, v46
	v_fmac_f32_e32 v120, v133, v47
	v_fmac_f32_e32 v121, v137, v47
	v_fmac_f32_e32 v122, v141, v47
	v_fmac_f32_e32 v123, v145, v47
	v_fmac_f32_e32 v124, v149, v47
	ds_read_b128 v[130:133], v83 offset:208
	ds_read_b128 v[134:137], v83 offset:8400
	ds_read_b128 v[138:141], v83 offset:16592
	ds_read_b128 v[142:145], v83 offset:24784
	ds_read_b128 v[146:149], v83 offset:32976
	s_waitcnt lgkmcnt(5)
	v_fmac_f32_e32 v120, v98, v48
	v_fmac_f32_e32 v121, v102, v48
	v_fmac_f32_e32 v122, v106, v48
	v_fmac_f32_e32 v123, v110, v48
	v_fmac_f32_e32 v124, v114, v48
	v_fmac_f32_e32 v120, v99, v49
	v_fmac_f32_e32 v121, v103, v49
	v_fmac_f32_e32 v122, v107, v49
	v_fmac_f32_e32 v123, v111, v49
	v_fmac_f32_e32 v124, v115, v49
	v_fmac_f32_e32 v120, v100, v50
	v_fmac_f32_e32 v121, v104, v50
	v_fmac_f32_e32 v122, v108, v50
	v_fmac_f32_e32 v123, v112, v50
	v_fmac_f32_e32 v124, v116, v50
	v_fmac_f32_e32 v120, v101, v51
	v_fmac_f32_e32 v121, v105, v51
	v_fmac_f32_e32 v122, v109, v51
	v_fmac_f32_e32 v123, v113, v51
	v_fmac_f32_e32 v124, v117, v51
	ds_read_b128 v[98:101], v83 offset:224
	ds_read_b128 v[102:105], v83 offset:8416
	ds_read_b128 v[106:109], v83 offset:16608
	ds_read_b128 v[110:113], v83 offset:24800
	ds_read_b128 v[114:117], v83 offset:32992
	s_waitcnt lgkmcnt(5)
	v_fmac_f32_e32 v120, v130, v52
	v_fmac_f32_e32 v121, v134, v52
	v_fmac_f32_e32 v122, v138, v52
	v_fmac_f32_e32 v123, v142, v52
	v_fmac_f32_e32 v124, v146, v52
	v_fmac_f32_e32 v120, v131, v53
	v_fmac_f32_e32 v121, v135, v53
	v_fmac_f32_e32 v122, v139, v53
	v_fmac_f32_e32 v123, v143, v53
	v_fmac_f32_e32 v124, v147, v53
	v_fmac_f32_e32 v120, v132, v54
	v_fmac_f32_e32 v121, v136, v54
	v_fmac_f32_e32 v122, v140, v54
	v_fmac_f32_e32 v123, v144, v54
	v_fmac_f32_e32 v124, v148, v54
	v_fmac_f32_e32 v120, v133, v55
	v_fmac_f32_e32 v121, v137, v55
	v_fmac_f32_e32 v122, v141, v55
	v_fmac_f32_e32 v123, v145, v55
	v_fmac_f32_e32 v124, v149, v55
	ds_read_b128 v[130:133], v83 offset:240
	ds_read_b128 v[134:137], v83 offset:8432
	ds_read_b128 v[138:141], v83 offset:16624
	ds_read_b128 v[142:145], v83 offset:24816
	ds_read_b128 v[146:149], v83 offset:33008
	s_waitcnt lgkmcnt(5)
	v_fmac_f32_e32 v120, v98, v56
	v_fmac_f32_e32 v121, v102, v56
	v_fmac_f32_e32 v122, v106, v56
	v_fmac_f32_e32 v123, v110, v56
	v_fmac_f32_e32 v124, v114, v56
	v_fmac_f32_e32 v120, v99, v57
	v_fmac_f32_e32 v121, v103, v57
	v_fmac_f32_e32 v122, v107, v57
	v_fmac_f32_e32 v123, v111, v57
	v_fmac_f32_e32 v124, v115, v57
	v_fmac_f32_e32 v120, v100, v58
	v_fmac_f32_e32 v121, v104, v58
	v_fmac_f32_e32 v122, v108, v58
	v_fmac_f32_e32 v123, v112, v58
	v_fmac_f32_e32 v124, v116, v58
	v_fmac_f32_e32 v120, v101, v59
	v_fmac_f32_e32 v121, v105, v59
	v_fmac_f32_e32 v122, v109, v59
	v_fmac_f32_e32 v123, v113, v59
	v_fmac_f32_e32 v124, v117, v59
	s_waitcnt lgkmcnt(0)
	v_fmac_f32_e32 v120, v130, v60
	v_fmac_f32_e32 v121, v134, v60
	v_fmac_f32_e32 v122, v138, v60
	v_fmac_f32_e32 v123, v142, v60
	v_fmac_f32_e32 v124, v146, v60
	v_fmac_f32_e32 v120, v131, v61
	v_fmac_f32_e32 v121, v135, v61
	v_fmac_f32_e32 v122, v139, v61
	v_fmac_f32_e32 v123, v143, v61
	v_fmac_f32_e32 v124, v147, v61
	v_fmac_f32_e32 v120, v132, v62
	v_fmac_f32_e32 v121, v136, v62
	v_fmac_f32_e32 v122, v140, v62
	v_fmac_f32_e32 v123, v144, v62
	v_fmac_f32_e32 v124, v148, v62
	v_fmac_f32_e32 v120, v133, v63
	v_fmac_f32_e32 v121, v137, v63
	v_fmac_f32_e32 v122, v141, v63
	v_fmac_f32_e32 v123, v145, v63
	v_fmac_f32_e32 v124, v149, v63
	v_mov_b32_e32 v60, v120
	v_mov_b32_e32 v61, v121
	v_mov_b32_e32 v4, v122
	v_mov_b32_e32 v5, v123
	v_mov_b32_e32 v81, v124
	ds_write2st64_b32 v88, v60, v61 offset0:160 offset1:161
	ds_write2st64_b32 v88, v4, v5 offset0:162 offset1:163
	ds_write_b32 v88, v81 offset:41984
	s_waitcnt lgkmcnt(0)
	s_barrier
; __device__ __forceinline__ void init_phase(const Args& a, LAS unsigned char* lds, int G) {
;     ...
;         if (tid < 320) {
;             const int r = tid >> 6, n2 = tid & 63; float s = 0.f;
; #pragma unroll
;             for (int k8 = 0; k8 < 8; ++k8) s += red[(k8 * 5 + r) * 64 + n2];
;             MOD[(size_t)(layer * 5 + r) * 6144 + n0 + n2] = s + a.in[5][layer * 6144 + n0 + n2];
;         }
	s_and_saveexec_b64 s[0:1], vcc
	s_cbranch_execz .LBB0_257
	s_mul_i32 s19, s18, 0x1800
	s_add_i32 s19, s19, s14
	v_or_b32_e32 v0, s19, v82
	v_ashrrev_i32_e32 v1, 31, v0
	v_lshl_add_u64 v[0:1], v[0:1], 2, s[12:13]
	global_load_dword v12, v[0:1], off
	v_add_u32_e32 v10, v86, v84
	ds_read2st64_b32 v[4:5], v10 offset0:160 offset1:165
	ds_read2st64_b32 v[6:7], v10 offset0:170 offset1:175
	ds_read2st64_b32 v[8:9], v10 offset0:180 offset1:185
	ds_read2st64_b32 v[10:11], v10 offset0:190 offset1:195
	v_mad_u64_u32 v[0:1], s[18:19], s18, 5, v[80:81]
	v_mov_b64_e32 v[2:3], s[4:5]
	v_mad_i64_i32 v[0:1], s[18:19], v0, s11, v[2:3]
	s_waitcnt lgkmcnt(3)
	v_add_f32_e32 v2, 0, v4
	v_add_f32_e32 v2, v2, v5
	s_waitcnt lgkmcnt(2)
	v_add_f32_e32 v2, v2, v6
	v_add_f32_e32 v2, v2, v7
	s_waitcnt lgkmcnt(1)
	v_add_f32_e32 v2, v2, v8
	v_add_f32_e32 v2, v2, v9
	s_waitcnt lgkmcnt(0)
	v_add_f32_e32 v2, v2, v10
	v_lshl_add_u64 v[0:1], s[14:15], 2, v[0:1]
	v_add_f32_e32 v2, v2, v11
	v_lshl_add_u64 v[0:1], v[0:1], 0, v[96:97]
	s_waitcnt vmcnt(0)
	v_add_f32_e32 v2, v2, v12
	global_store_dword v[0:1], v2, off
	s_branch .LBB0_257

; #define LAS __attribute__((address_space(3)))
; __device__ __forceinline__ void transpose_layer(const Args& a, int layer, LAS unsigned char* lds, int gw, int NGW, int wave, int lane) {
;     LAS float* scr = (LAS float*)(lds + wave * 16640);
;     bf16_t* WIN = (bf16_t*)(a.ws + WS_WIN); bf16_t* WOUT = (bf16_t*)(a.ws + WS_WOUT); bf16_t* WG = (bf16_t*)(a.ws + WS_WG);
;     const int kind = layer % 3, j = layer / 3;
;     if (kind == 0) {
;         const float* win = a.in[8] + (size_t)j * DM * 16384; const float* wout = a.in[10] + (size_t)j * DI * DM;
;         const int n_in = (DM / 64) * (16384 / 64), n_out = (DI / 64) * (DM / 64);
;         for (int it = gw; it < n_in + n_out; it += NGW) {
;             if (it < n_in) tr_item(win, DM, 16384, WIN, 0x2310, scr, it, lane);
;             else tr_item(wout, DI, DM, WOUT, 0x43210, scr, it - n_in, lane);
.LBB0_264:
	s_or_b64 exec, exec, s[0:1]
	s_cmpk_gt_i32 s22, 0x27ff
	s_mov_b32 s23, 0x20000
	s_mov_b32 s24, 0x10000
	s_mov_b32 s25, 0x1e000
	s_barrier
	s_branch .LBB0_271
	v_readlane_b32 s5, v250, 3
	s_mul_i32 s0, s5, 0x4100
	v_lshlrev_b32_e32 v0, 3, v194
	s_add_i32 s4, s0, 0
	v_and_b32_e32 v0, 56, v0
	v_readlane_b32 s0, v250, 1
	v_lshlrev_b32_e32 v96, 1, v0
	v_readlane_b32 s1, v250, 2
	v_mul_u32_u24_e32 v4, 0x104, v0
	v_lshrrev_b32_e32 v7, 3, v194
	v_lshl_add_u64 v[2:3], s[0:1], 0, v[96:97]
	s_mov_b64 s[0:1], 0x7e00000
	v_lshl_add_u64 v[0:1], v[2:3], 0, s[0:1]
	s_mov_b64 s[0:1], 0x2e00000
	v_lshl_add_u64 v[2:3], v[2:3], 0, s[0:1]
	v_readlane_b32 s0, v251, 5
	v_lshlrev_b32_e32 v5, 2, v7
	s_add_i32 s6, s0, s5
	s_lshl_b32 s0, s5, 6
	v_readlane_b32 s1, v252, 7
	v_lshl_add_u32 v6, v194, 2, s4
	v_add3_u32 v8, s4, v4, v5
	s_add_i32 s7, s1, s0
	s_branch .LBB0_267

; #define LAS __attribute__((address_space(3)))
; __device__ __forceinline__ void tr_item(const float* __restrict__ W, int K, int N, bf16_t* WT, int segperm, LAS float* scr, int item, int lane) {
;     const int nblk = N >> 6, kb = item / nblk, nb = item - kb * nblk, k0 = kb << 6, n0 = nb << 6;
;     const float* src = W + (size_t)k0 * N + n0 + lane;
;     float tv[64];
; #pragma unroll
;     for (int i = 0; i < 64; ++i) tv[i] = src[(size_t)i * N];
; #pragma unroll
;     for (int i = 0; i < 64; ++i) scr[i * 65 + lane] = tv[i];
; __device__ __forceinline__ void transpose_layer(const Args& a, int layer, LAS unsigned char* lds, int gw, int NGW, int wave, int lane) {
;     LAS float* scr = (LAS float*)(lds + wave * 16640);
;     bf16_t* WIN = (bf16_t*)(a.ws + WS_WIN); bf16_t* WOUT = (bf16_t*)(a.ws + WS_WOUT); bf16_t* WG = (bf16_t*)(a.ws + WS_WG);
;     const int kind = layer % 3, j = layer / 3;
;     if (kind == 0) {
;         const float* win = a.in[8] + (size_t)j * DM * 16384; const float* wout = a.in[10] + (size_t)j * DI * DM;
;         const int n_in = (DM / 64) * (16384 / 64), n_out = (DI / 64) * (DM / 64);
;         for (int it = gw; it < n_in + n_out; it += NGW) {
;             if (it < n_in) tr_item(win, DM, 16384, WIN, 0x2310, scr, it, lane);
;             else tr_item(wout, DI, DM, WOUT, 0x43210, scr, it - n_in, lane);
.LBB0_421:
	v_readlane_b32 s28, v251, 50
	s_cmp_eq_u32 s28, 0
	s_cbranch_scc1 .Ltr_go0
	s_cmp_lg_u32 s28, 4
	s_cbranch_scc1 .Ltr_done
	s_mov_b32 s18, 64
	s_branch .Ltr_go
.Ltr_go0:
	s_mov_b32 s18, 0
.Ltr_go:
	v_readlane_b32 s15, v251, 49
	v_readlane_b32 s19, v250, 3
	s_cmp_lt_u32 s15, s18
	s_cbranch_scc1 .Ltr_done
	v_writelane_b32 v255, s36, 0
	v_writelane_b32 v255, s37, 1
	v_writelane_b32 v255, s38, 2
	v_writelane_b32 v255, s39, 3
	v_writelane_b32 v255, s40, 4
	v_writelane_b32 v255, s41, 5
	v_writelane_b32 v255, s42, 6
	v_writelane_b32 v255, s43, 7
	v_writelane_b32 v255, s44, 8
	v_writelane_b32 v255, s45, 9
	v_writelane_b32 v255, s46, 10
	v_writelane_b32 v255, s47, 11
	v_writelane_b32 v255, s48, 12
	v_writelane_b32 v255, s49, 13
	v_writelane_b32 v255, s50, 14
	v_writelane_b32 v255, s51, 15
	v_writelane_b32 v255, s52, 16
	v_writelane_b32 v255, s53, 17
	v_writelane_b32 v255, s54, 18
	v_writelane_b32 v255, s55, 19
	v_writelane_b32 v255, s56, 20
	v_writelane_b32 v255, s57, 21
	v_writelane_b32 v255, s58, 22
	v_writelane_b32 v255, s59, 23
	v_writelane_b32 v255, s60, 24
	v_writelane_b32 v255, s61, 25
	v_writelane_b32 v255, s62, 26
	v_writelane_b32 v255, s63, 27
	s_sub_i32 s15, s15, s18
	s_lshl_b32 s15, s15, 3
	s_add_i32 s62, s15, s19
	v_readlane_b32 s37, v252, 2
	v_readlane_b32 s54, v252, 0
	v_readlane_b32 s55, v252, 1
	s_sub_i32 s37, s37, s18
	s_lshl_b32 s37, s37, 3
	s_mov_b32 s61, 0
	v_lshlrev_b32_e32 v80, 2, v210
	s_add_u32 s40, s54, 0x2e00000
	s_addc_u32 s41, s55, 0
	s_cmp_eq_u32 s28, 4
	s_cbranch_scc1 .Ltr_p1
	s_movk_i32 s38, 0x2000
	s_movk_i32 s39, 0x100
	s_mov_b32 s42, 0x1000000
	s_mov_b32 s43, 0x10000
	s_mov_b32 s44, 0x42310
	s_mov_b32 s60, 18
	v_readlane_b32 s46, v251, 13
	v_readlane_b32 s47, v251, 14
	s_branch .Ltr_start
.Ltr_p1:
	s_movk_i32 s38, 0x1000
	s_movk_i32 s39, 0x80
	s_mov_b32 s42, 0x2000000
	s_mov_b32 s43, 0x8000
	s_mov_b32 s44, 0x43210
	s_mov_b32 s60, 18
	v_readlane_b32 s46, v251, 19
	v_readlane_b32 s47, v251, 20
.Ltr_start:
	s_sub_i32 s45, s60, 6
	s_mov_b32 s36, s62
	v_lshlrev_b32_e32 v81, s45, v210
	s_cmp_ge_u32 s36, s38
	s_cbranch_scc1 .Ltr_exit
	s_mul_hi_u32 s48, s36, s42
	s_mul_i32 s49, s48, s39
	s_sub_i32 s49, s36, s49
	s_lshr_b32 s50, s49, 6
	s_lshl_b32 s51, s50, 2
	s_lshr_b32 s51, s44, s51
	s_and_b32 s51, s51, 15
	s_sub_i32 s51, s51, s50
	s_lshl_b32 s51, s51, 6
	s_add_i32 s51, s51, s49
	s_lshl_b32 s52, s51, s60
	s_lshl_b32 s53, s48, 7
	s_add_u32 s52, s52, s53
	s_add_u32 s54, s40, s52
	s_addc_u32 s55, s41, 0
	s_lshl_b32 s52, s48, 6
	s_mul_i32 s52, s52, s43
	s_lshl_b32 s53, s49, 8
	s_add_u32 s52, s52, s53
	s_add_u32 s56, s46, s52
	s_addc_u32 s57, s47, 0
	global_load_dword v0, v80, s[56:57]
	s_add_u32 s56, s56, s43
	s_addc_u32 s57, s57, 0
	global_load_dword v1, v80, s[56:57]
	s_add_u32 s56, s56, s43
	s_addc_u32 s57, s57, 0
	global_load_dword v2, v80, s[56:57]
	s_add_u32 s56, s56, s43
	s_addc_u32 s57, s57, 0
	global_load_dword v3, v80, s[56:57]
	s_add_u32 s56, s56, s43
	s_addc_u32 s57, s57, 0
	global_load_dword v4, v80, s[56:57]
	s_add_u32 s56, s56, s43
	s_addc_u32 s57, s57, 0
	global_load_dword v5, v80, s[56:57]
	s_add_u32 s56, s56, s43
	s_addc_u32 s57, s57, 0
	global_load_dword v6, v80, s[56:57]
	s_add_u32 s56, s56, s43
	s_addc_u32 s57, s57, 0
	global_load_dword v7, v80, s[56:57]
	s_add_u32 s56, s56, s43
	s_addc_u32 s57, s57, 0
	global_load_dword v8, v80, s[56:57]
	s_add_u32 s56, s56, s43
	s_addc_u32 s57, s57, 0
	global_load_dword v9, v80, s[56:57]
	s_add_u32 s56, s56, s43
	s_addc_u32 s57, s57, 0
	global_load_dword v10, v80, s[56:57]
	s_add_u32 s56, s56, s43
	s_addc_u32 s57, s57, 0
	global_load_dword v11, v80, s[56:57]
	s_add_u32 s56, s56, s43
	s_addc_u32 s57, s57, 0
	global_load_dword v12, v80, s[56:57]
	s_add_u32 s56, s56, s43
	s_addc_u32 s57, s57, 0
	global_load_dword v13, v80, s[56:57]
	s_add_u32 s56, s56, s43
	s_addc_u32 s57, s57, 0
	global_load_dword v14, v80, s[56:57]
	s_add_u32 s56, s56, s43
	s_addc_u32 s57, s57, 0
	global_load_dword v15, v80, s[56:57]
	s_add_u32 s56, s56, s43
	s_addc_u32 s57, s57, 0
	global_load_dword v16, v80, s[56:57]
	s_add_u32 s56, s56, s43
	s_addc_u32 s57, s57, 0
	global_load_dword v17, v80, s[56:57]
	s_add_u32 s56, s56, s43
	s_addc_u32 s57, s57, 0
	global_load_dword v18, v80, s[56:57]
	s_add_u32 s56, s56, s43
	s_addc_u32 s57, s57, 0
	global_load_dword v19, v80, s[56:57]
	s_add_u32 s56, s56, s43
	s_addc_u32 s57, s57, 0
	global_load_dword v20, v80, s[56:57]
	s_add_u32 s56, s56, s43
	s_addc_u32 s57, s57, 0
	global_load_dword v21, v80, s[56:57]
	s_add_u32 s56, s56, s43
	s_addc_u32 s57, s57, 0
	global_load_dword v22, v80, s[56:57]
	s_add_u32 s56, s56, s43
	s_addc_u32 s57, s57, 0
	global_load_dword v23, v80, s[56:57]
	s_add_u32 s56, s56, s43
	s_addc_u32 s57, s57, 0
	global_load_dword v24, v80, s[56:57]
	s_add_u32 s56, s56, s43
	s_addc_u32 s57, s57, 0
	global_load_dword v25, v80, s[56:57]
	s_add_u32 s56, s56, s43
	s_addc_u32 s57, s57, 0
	global_load_dword v26, v80, s[56:57]
	s_add_u32 s56, s56, s43
	s_addc_u32 s57, s57, 0
	global_load_dword v27, v80, s[56:57]
	s_add_u32 s56, s56, s43
	s_addc_u32 s57, s57, 0
	global_load_dword v28, v80, s[56:57]
	s_add_u32 s56, s56, s43
	s_addc_u32 s57, s57, 0
	global_load_dword v29, v80, s[56:57]
	s_add_u32 s56, s56, s43
	s_addc_u32 s57, s57, 0
	global_load_dword v30, v80, s[56:57]
	s_add_u32 s56, s56, s43
	s_addc_u32 s57, s57, 0
	global_load_dword v31, v80, s[56:57]
	s_add_u32 s56, s56, s43
	s_addc_u32 s57, s57, 0
	global_load_dword v32, v80, s[56:57]
	s_add_u32 s56, s56, s43
	s_addc_u32 s57, s57, 0
	global_load_dword v33, v80, s[56:57]
	s_add_u32 s56, s56, s43
	s_addc_u32 s57, s57, 0
	global_load_dword v34, v80, s[56:57]
	s_add_u32 s56, s56, s43
; #define LAS __attribute__((address_space(3)))
; #define LDS_WAIT() asm volatile("s_waitcnt lgkmcnt(0)" ::: "memory")
; __device__ __forceinline__ void tr_item(const float* __restrict__ W, int K, int N, bf16_t* WT, int segperm, LAS float* scr, int item, int lane) {
;     const int nblk = N >> 6, kb = item / nblk, nb = item - kb * nblk, k0 = kb << 6, n0 = nb << 6;
;     const float* src = W + (size_t)k0 * N + n0 + lane;
;     float tv[64];
; #pragma unroll
;     for (int i = 0; i < 64; ++i) tv[i] = src[(size_t)i * N];
; #pragma unroll
;     for (int i = 0; i < 64; ++i) scr[i * 65 + lane] = tv[i];
;     LDS_WAIT();
;     const int seg = n0 >> 12, dseg = (segperm >> (4 * seg)) & 15, drow0 = n0 + (dseg - seg) * 4096;
;     const int c = lane & 7;
; #pragma unroll
;     for (int j = 0; j < 8; ++j) {
;         const int n = (lane >> 3) + 8 * j; const LAS float* s = scr + (8 * c) * 65 + n;
;         u32x4 o; o.x = pk2(s[0], s[65]); o.y = pk2(s[130], s[195]); o.z = pk2(s[260], s[325]); o.w = pk2(s[390], s[455]);
;         *(u32x4*)(WT + (size_t)(drow0 + n) * K + k0 + 8 * c) = o;
;     }
	s_addc_u32 s57, s57, 0
	global_load_dword v35, v80, s[56:57]
	s_add_u32 s56, s56, s43
	s_addc_u32 s57, s57, 0
	global_load_dword v36, v80, s[56:57]
	s_add_u32 s56, s56, s43
	s_addc_u32 s57, s57, 0
	global_load_dword v37, v80, s[56:57]
	s_add_u32 s56, s56, s43
	s_addc_u32 s57, s57, 0
	global_load_dword v38, v80, s[56:57]
	s_add_u32 s56, s56, s43
	s_addc_u32 s57, s57, 0
	global_load_dword v39, v80, s[56:57]
	s_add_u32 s56, s56, s43
	s_addc_u32 s57, s57, 0
	global_load_dword v40, v80, s[56:57]
	s_add_u32 s56, s56, s43
	s_addc_u32 s57, s57, 0
	global_load_dword v41, v80, s[56:57]
	s_add_u32 s56, s56, s43
	s_addc_u32 s57, s57, 0
	global_load_dword v42, v80, s[56:57]
	s_add_u32 s56, s56, s43
	s_addc_u32 s57, s57, 0
	global_load_dword v43, v80, s[56:57]
	s_add_u32 s56, s56, s43
	s_addc_u32 s57, s57, 0
	global_load_dword v44, v80, s[56:57]
	s_add_u32 s56, s56, s43
	s_addc_u32 s57, s57, 0
	global_load_dword v45, v80, s[56:57]
	s_add_u32 s56, s56, s43
	s_addc_u32 s57, s57, 0
	global_load_dword v46, v80, s[56:57]
	s_add_u32 s56, s56, s43
	s_addc_u32 s57, s57, 0
	global_load_dword v47, v80, s[56:57]
	s_add_u32 s56, s56, s43
	s_addc_u32 s57, s57, 0
	global_load_dword v48, v80, s[56:57]
	s_add_u32 s56, s56, s43
	s_addc_u32 s57, s57, 0
	global_load_dword v49, v80, s[56:57]
	s_add_u32 s56, s56, s43
	s_addc_u32 s57, s57, 0
	global_load_dword v50, v80, s[56:57]
	s_add_u32 s56, s56, s43
	s_addc_u32 s57, s57, 0
	global_load_dword v51, v80, s[56:57]
	s_add_u32 s56, s56, s43
	s_addc_u32 s57, s57, 0
	global_load_dword v52, v80, s[56:57]
	s_add_u32 s56, s56, s43
	s_addc_u32 s57, s57, 0
	global_load_dword v53, v80, s[56:57]
	s_add_u32 s56, s56, s43
	s_addc_u32 s57, s57, 0
	global_load_dword v54, v80, s[56:57]
	s_add_u32 s56, s56, s43
	s_addc_u32 s57, s57, 0
	global_load_dword v55, v80, s[56:57]
	s_add_u32 s56, s56, s43
	s_addc_u32 s57, s57, 0
	global_load_dword v56, v80, s[56:57]
	s_add_u32 s56, s56, s43
	s_addc_u32 s57, s57, 0
	global_load_dword v57, v80, s[56:57]
	s_add_u32 s56, s56, s43
	s_addc_u32 s57, s57, 0
	global_load_dword v58, v80, s[56:57]
	s_add_u32 s56, s56, s43
	s_addc_u32 s57, s57, 0
	global_load_dword v59, v80, s[56:57]
	s_add_u32 s56, s56, s43
	s_addc_u32 s57, s57, 0
	global_load_dword v60, v80, s[56:57]
	s_add_u32 s56, s56, s43
	s_addc_u32 s57, s57, 0
	global_load_dword v61, v80, s[56:57]
	s_add_u32 s56, s56, s43
	s_addc_u32 s57, s57, 0
	global_load_dword v62, v80, s[56:57]
	s_add_u32 s56, s56, s43
	s_addc_u32 s57, s57, 0
	global_load_dword v63, v80, s[56:57]
	s_add_u32 s56, s56, s43
	s_addc_u32 s57, s57, 0
	s_waitcnt vmcnt(32)
	v_cvt_pk_bf16_f32 v64, v0, v1
	v_cvt_pk_bf16_f32 v65, v2, v3
	v_cvt_pk_bf16_f32 v66, v4, v5
	v_cvt_pk_bf16_f32 v67, v6, v7
	v_cvt_pk_bf16_f32 v68, v8, v9
	v_cvt_pk_bf16_f32 v69, v10, v11
	v_cvt_pk_bf16_f32 v70, v12, v13
	v_cvt_pk_bf16_f32 v71, v14, v15
	v_cvt_pk_bf16_f32 v72, v16, v17
	v_cvt_pk_bf16_f32 v73, v18, v19
	v_cvt_pk_bf16_f32 v74, v20, v21
	v_cvt_pk_bf16_f32 v75, v22, v23
	v_cvt_pk_bf16_f32 v76, v24, v25
	v_cvt_pk_bf16_f32 v77, v26, v27
	v_cvt_pk_bf16_f32 v78, v28, v29
	v_cvt_pk_bf16_f32 v79, v30, v31
	global_store_dwordx4 v81, v[64:67], s[54:55]
	global_store_dwordx4 v81, v[68:71], s[54:55] offset:16
	global_store_dwordx4 v81, v[72:75], s[54:55] offset:32
	global_store_dwordx4 v81, v[76:79], s[54:55] offset:48
.Ltr_loop:
	s_add_i32 s45, s36, s37
	s_cmp_ge_u32 s45, s38
	s_cbranch_scc1 .Ltr_last
	s_mul_hi_u32 s48, s45, s42
	s_mul_i32 s49, s48, s39
	s_sub_i32 s49, s45, s49
	s_lshr_b32 s50, s49, 6
	s_lshl_b32 s51, s50, 2
	s_lshr_b32 s51, s44, s51
	s_and_b32 s51, s51, 15
	s_sub_i32 s51, s51, s50
	s_lshl_b32 s51, s51, 6
	s_add_i32 s51, s51, s49
	s_lshl_b32 s52, s51, s60
	s_lshl_b32 s53, s48, 7
	s_add_u32 s52, s52, s53
	s_add_u32 s58, s40, s52
	s_addc_u32 s59, s41, 0
	s_lshl_b32 s52, s48, 6
	s_mul_i32 s52, s52, s43
	s_lshl_b32 s53, s49, 8
	s_add_u32 s52, s52, s53
	s_add_u32 s56, s46, s52
	s_addc_u32 s57, s47, 0
	global_load_dword v0, v80, s[56:57]
	s_add_u32 s56, s56, s43
	s_addc_u32 s57, s57, 0
	global_load_dword v1, v80, s[56:57]
	s_add_u32 s56, s56, s43
	s_addc_u32 s57, s57, 0
	global_load_dword v2, v80, s[56:57]
	s_add_u32 s56, s56, s43
	s_addc_u32 s57, s57, 0
	global_load_dword v3, v80, s[56:57]
	s_add_u32 s56, s56, s43
	s_addc_u32 s57, s57, 0
	global_load_dword v4, v80, s[56:57]
	s_add_u32 s56, s56, s43
	s_addc_u32 s57, s57, 0
	global_load_dword v5, v80, s[56:57]
	s_add_u32 s56, s56, s43
	s_addc_u32 s57, s57, 0
	global_load_dword v6, v80, s[56:57]
	s_add_u32 s56, s56, s43
	s_addc_u32 s57, s57, 0
	global_load_dword v7, v80, s[56:57]
	s_add_u32 s56, s56, s43
	s_addc_u32 s57, s57, 0
	global_load_dword v8, v80, s[56:57]
	s_add_u32 s56, s56, s43
	s_addc_u32 s57, s57, 0
	global_load_dword v9, v80, s[56:57]
	s_add_u32 s56, s56, s43
	s_addc_u32 s57, s57, 0
	global_load_dword v10, v80, s[56:57]
	s_add_u32 s56, s56, s43
	s_addc_u32 s57, s57, 0
	global_load_dword v11, v80, s[56:57]
	s_add_u32 s56, s56, s43
	s_addc_u32 s57, s57, 0
	global_load_dword v12, v80, s[56:57]
	s_add_u32 s56, s56, s43
	s_addc_u32 s57, s57, 0
	global_load_dword v13, v80, s[56:57]
	s_add_u32 s56, s56, s43
	s_addc_u32 s57, s57, 0
	global_load_dword v14, v80, s[56:57]
	s_add_u32 s56, s56, s43
	s_addc_u32 s57, s57, 0
	global_load_dword v15, v80, s[56:57]
	s_add_u32 s56, s56, s43
	s_addc_u32 s57, s57, 0
	global_load_dword v16, v80, s[56:57]
	s_add_u32 s56, s56, s43
	s_addc_u32 s57, s57, 0
	global_load_dword v17, v80, s[56:57]
	s_add_u32 s56, s56, s43
	s_addc_u32 s57, s57, 0
	global_load_dword v18, v80, s[56:57]
	s_add_u32 s56, s56, s43
	s_addc_u32 s57, s57, 0
	global_load_dword v19, v80, s[56:57]
	s_add_u32 s56, s56, s43
	s_addc_u32 s57, s57, 0
	global_load_dword v20, v80, s[56:57]
	s_add_u32 s56, s56, s43
	s_addc_u32 s57, s57, 0
	global_load_dword v21, v80, s[56:57]
	s_add_u32 s56, s56, s43
	s_addc_u32 s57, s57, 0
	global_load_dword v22, v80, s[56:57]
	s_add_u32 s56, s56, s43
	s_addc_u32 s57, s57, 0
	global_load_dword v23, v80, s[56:57]
	s_add_u32 s56, s56, s43
	s_addc_u32 s57, s57, 0
	global_load_dword v24, v80, s[56:57]
	s_add_u32 s56, s56, s43
	s_addc_u32 s57, s57, 0
	global_load_dword v25, v80, s[56:57]
	s_add_u32 s56, s56, s43
	s_addc_u32 s57, s57, 0
	global_load_dword v26, v80, s[56:57]
	s_add_u32 s56, s56, s43
	s_addc_u32 s57, s57, 0
	global_load_dword v27, v80, s[56:57]
	s_add_u32 s56, s56, s43
	s_addc_u32 s57, s57, 0
	global_load_dword v28, v80, s[56:57]
	s_add_u32 s56, s56, s43
	s_addc_u32 s57, s57, 0
	global_load_dword v29, v80, s[56:57]
	s_add_u32 s56, s56, s43
	s_addc_u32 s57, s57, 0
	global_load_dword v30, v80, s[56:57]
	s_add_u32 s56, s56, s43
	s_addc_u32 s57, s57, 0
	global_load_dword v31, v80, s[56:57]
	s_add_u32 s56, s56, s43
	s_addc_u32 s57, s57, 0
	s_waitcnt vmcnt(36)
; #define LAS __attribute__((address_space(3)))
; #define LDS_WAIT() asm volatile("s_waitcnt lgkmcnt(0)" ::: "memory")
; __device__ __forceinline__ void tr_item(const float* __restrict__ W, int K, int N, bf16_t* WT, int segperm, LAS float* scr, int item, int lane) {
;     const int nblk = N >> 6, kb = item / nblk, nb = item - kb * nblk, k0 = kb << 6, n0 = nb << 6;
;     const float* src = W + (size_t)k0 * N + n0 + lane;
;     float tv[64];
; #pragma unroll
;     for (int i = 0; i < 64; ++i) tv[i] = src[(size_t)i * N];
; #pragma unroll
;     for (int i = 0; i < 64; ++i) scr[i * 65 + lane] = tv[i];
;     LDS_WAIT();
;     const int seg = n0 >> 12, dseg = (segperm >> (4 * seg)) & 15, drow0 = n0 + (dseg - seg) * 4096;
;     const int c = lane & 7;
; #pragma unroll
;     for (int j = 0; j < 8; ++j) {
;         const int n = (lane >> 3) + 8 * j; const LAS float* s = scr + (8 * c) * 65 + n;
;         u32x4 o; o.x = pk2(s[0], s[65]); o.y = pk2(s[130], s[195]); o.z = pk2(s[260], s[325]); o.w = pk2(s[390], s[455]);
;         *(u32x4*)(WT + (size_t)(drow0 + n) * K + k0 + 8 * c) = o;
;     }
	v_cvt_pk_bf16_f32 v64, v32, v33
	v_cvt_pk_bf16_f32 v65, v34, v35
	v_cvt_pk_bf16_f32 v66, v36, v37
	v_cvt_pk_bf16_f32 v67, v38, v39
	v_cvt_pk_bf16_f32 v68, v40, v41
	v_cvt_pk_bf16_f32 v69, v42, v43
	v_cvt_pk_bf16_f32 v70, v44, v45
	v_cvt_pk_bf16_f32 v71, v46, v47
	v_cvt_pk_bf16_f32 v72, v48, v49
	v_cvt_pk_bf16_f32 v73, v50, v51
	v_cvt_pk_bf16_f32 v74, v52, v53
	v_cvt_pk_bf16_f32 v75, v54, v55
	v_cvt_pk_bf16_f32 v76, v56, v57
	v_cvt_pk_bf16_f32 v77, v58, v59
	v_cvt_pk_bf16_f32 v78, v60, v61
	v_cvt_pk_bf16_f32 v79, v62, v63
	global_store_dwordx4 v81, v[64:67], s[54:55] offset:64
	global_store_dwordx4 v81, v[68:71], s[54:55] offset:80
	global_store_dwordx4 v81, v[72:75], s[54:55] offset:96
	global_store_dwordx4 v81, v[76:79], s[54:55] offset:112
	s_mov_b32 s36, s45
	s_mov_b64 s[54:55], s[58:59]
	global_load_dword v32, v80, s[56:57]
	s_add_u32 s56, s56, s43
	s_addc_u32 s57, s57, 0
	global_load_dword v33, v80, s[56:57]
	s_add_u32 s56, s56, s43
	s_addc_u32 s57, s57, 0
	global_load_dword v34, v80, s[56:57]
	s_add_u32 s56, s56, s43
	s_addc_u32 s57, s57, 0
	global_load_dword v35, v80, s[56:57]
	s_add_u32 s56, s56, s43
	s_addc_u32 s57, s57, 0
	global_load_dword v36, v80, s[56:57]
	s_add_u32 s56, s56, s43
	s_addc_u32 s57, s57, 0
	global_load_dword v37, v80, s[56:57]
	s_add_u32 s56, s56, s43
	s_addc_u32 s57, s57, 0
	global_load_dword v38, v80, s[56:57]
	s_add_u32 s56, s56, s43
	s_addc_u32 s57, s57, 0
	global_load_dword v39, v80, s[56:57]
	s_add_u32 s56, s56, s43
	s_addc_u32 s57, s57, 0
	global_load_dword v40, v80, s[56:57]
	s_add_u32 s56, s56, s43
	s_addc_u32 s57, s57, 0
	global_load_dword v41, v80, s[56:57]
	s_add_u32 s56, s56, s43
	s_addc_u32 s57, s57, 0
	global_load_dword v42, v80, s[56:57]
	s_add_u32 s56, s56, s43
	s_addc_u32 s57, s57, 0
	global_load_dword v43, v80, s[56:57]
	s_add_u32 s56, s56, s43
	s_addc_u32 s57, s57, 0
	global_load_dword v44, v80, s[56:57]
	s_add_u32 s56, s56, s43
	s_addc_u32 s57, s57, 0
	global_load_dword v45, v80, s[56:57]
	s_add_u32 s56, s56, s43
	s_addc_u32 s57, s57, 0
	global_load_dword v46, v80, s[56:57]
	s_add_u32 s56, s56, s43
	s_addc_u32 s57, s57, 0
	global_load_dword v47, v80, s[56:57]
	s_add_u32 s56, s56, s43
	s_addc_u32 s57, s57, 0
	global_load_dword v48, v80, s[56:57]
	s_add_u32 s56, s56, s43
	s_addc_u32 s57, s57, 0
	global_load_dword v49, v80, s[56:57]
	s_add_u32 s56, s56, s43
	s_addc_u32 s57, s57, 0
	global_load_dword v50, v80, s[56:57]
	s_add_u32 s56, s56, s43
	s_addc_u32 s57, s57, 0
	global_load_dword v51, v80, s[56:57]
	s_add_u32 s56, s56, s43
	s_addc_u32 s57, s57, 0
	global_load_dword v52, v80, s[56:57]
	s_add_u32 s56, s56, s43
	s_addc_u32 s57, s57, 0
	global_load_dword v53, v80, s[56:57]
	s_add_u32 s56, s56, s43
	s_addc_u32 s57, s57, 0
	global_load_dword v54, v80, s[56:57]
	s_add_u32 s56, s56, s43
	s_addc_u32 s57, s57, 0
	global_load_dword v55, v80, s[56:57]
	s_add_u32 s56, s56, s43
	s_addc_u32 s57, s57, 0
	global_load_dword v56, v80, s[56:57]
	s_add_u32 s56, s56, s43
	s_addc_u32 s57, s57, 0
	global_load_dword v57, v80, s[56:57]
	s_add_u32 s56, s56, s43
	s_addc_u32 s57, s57, 0
	global_load_dword v58, v80, s[56:57]
	s_add_u32 s56, s56, s43
	s_addc_u32 s57, s57, 0
	global_load_dword v59, v80, s[56:57]
	s_add_u32 s56, s56, s43
	s_addc_u32 s57, s57, 0
	global_load_dword v60, v80, s[56:57]
	s_add_u32 s56, s56, s43
	s_addc_u32 s57, s57, 0
	global_load_dword v61, v80, s[56:57]
	s_add_u32 s56, s56, s43
	s_addc_u32 s57, s57, 0
	global_load_dword v62, v80, s[56:57]
	s_add_u32 s56, s56, s43
	s_addc_u32 s57, s57, 0
	global_load_dword v63, v80, s[56:57]
	s_add_u32 s56, s56, s43
	s_addc_u32 s57, s57, 0
	s_waitcnt vmcnt(36)
	v_cvt_pk_bf16_f32 v64, v0, v1
	v_cvt_pk_bf16_f32 v65, v2, v3
	v_cvt_pk_bf16_f32 v66, v4, v5
	v_cvt_pk_bf16_f32 v67, v6, v7
	v_cvt_pk_bf16_f32 v68, v8, v9
	v_cvt_pk_bf16_f32 v69, v10, v11
	v_cvt_pk_bf16_f32 v70, v12, v13
	v_cvt_pk_bf16_f32 v71, v14, v15
	v_cvt_pk_bf16_f32 v72, v16, v17
	v_cvt_pk_bf16_f32 v73, v18, v19
	v_cvt_pk_bf16_f32 v74, v20, v21
	v_cvt_pk_bf16_f32 v75, v22, v23
	v_cvt_pk_bf16_f32 v76, v24, v25
	v_cvt_pk_bf16_f32 v77, v26, v27
	v_cvt_pk_bf16_f32 v78, v28, v29
	v_cvt_pk_bf16_f32 v79, v30, v31
	global_store_dwordx4 v81, v[64:67], s[54:55]
	global_store_dwordx4 v81, v[68:71], s[54:55] offset:16
	global_store_dwordx4 v81, v[72:75], s[54:55] offset:32
	global_store_dwordx4 v81, v[76:79], s[54:55] offset:48
	s_branch .Ltr_loop

; #define LAS __attribute__((address_space(3)))
; __device__ __forceinline__ void transpose_layer(const Args& a, int layer, LAS unsigned char* lds, int gw, int NGW, int wave, int lane) {
;     LAS float* scr = (LAS float*)(lds + wave * 16640);
;     bf16_t* WIN = (bf16_t*)(a.ws + WS_WIN); bf16_t* WOUT = (bf16_t*)(a.ws + WS_WOUT); bf16_t* WG = (bf16_t*)(a.ws + WS_WG);
;     const int kind = layer % 3, j = layer / 3;
;     if (kind == 0) {
;         const float* win = a.in[8] + (size_t)j * DM * 16384; const float* wout = a.in[10] + (size_t)j * DI * DM;
;         const int n_in = (DM / 64) * (16384 / 64), n_out = (DI / 64) * (DM / 64);
;         for (int it = gw; it < n_in + n_out; it += NGW) {
;             if (it < n_in) tr_item(win, DM, 16384, WIN, 0x2310, scr, it, lane);
;             else tr_item(wout, DI, DM, WOUT, 0x43210, scr, it - n_in, lane);
;         }
.Ltr_exit:
	s_cmp_lg_u32 s28, 0
	s_cbranch_scc1 .Ltr_fin
	s_cmp_lg_u32 s61, 0
	s_cbranch_scc1 .Ltr_fin
	s_mov_b32 s61, 1
	v_readlane_b32 s40, v252, 0
	v_readlane_b32 s41, v252, 1
	s_movk_i32 s38, 0x800
	s_movk_i32 s39, 0x20
	s_mov_b32 s42, 0x8000000
	s_mov_b32 s43, 0x2000
	s_mov_b32 s44, 0x43210
	s_mov_b32 s60, 19
	v_readlane_b32 s46, v251, 17
	v_readlane_b32 s47, v251, 18
	s_add_u32 s40, s40, 0x7e00000
	s_addc_u32 s41, s41, 0
	s_branch .Ltr_start
.Ltr_fin:
	v_readlane_b32 s36, v255, 0
	v_readlane_b32 s37, v255, 1
	v_readlane_b32 s38, v255, 2
	v_readlane_b32 s39, v255, 3
	v_readlane_b32 s40, v255, 4
	v_readlane_b32 s41, v255, 5
	v_readlane_b32 s42, v255, 6
	v_readlane_b32 s43, v255, 7
	v_readlane_b32 s44, v255, 8
	v_readlane_b32 s45, v255, 9
	v_readlane_b32 s46, v255, 10
	v_readlane_b32 s47, v255, 11
	v_readlane_b32 s48, v255, 12
	v_readlane_b32 s49, v255, 13
	v_readlane_b32 s50, v255, 14
	v_readlane_b32 s51, v255, 15
	v_readlane_b32 s52, v255, 16
	v_readlane_b32 s53, v255, 17
	v_readlane_b32 s54, v255, 18
	v_readlane_b32 s55, v255, 19
	v_readlane_b32 s56, v255, 20
	v_readlane_b32 s57, v255, 21
	v_readlane_b32 s58, v255, 22
	v_readlane_b32 s59, v255, 23
	v_readlane_b32 s60, v255, 24
	v_readlane_b32 s61, v255, 25
	v_readlane_b32 s62, v255, 26
	v_readlane_b32 s63, v255, 27
	s_nop 4
